# P10: one work queue per XCD (batch-head index mod 8 = XCC id) so workgroups sharing an L2 stream the same K/V tiles; global queue kept when the census does not find 8 XCDs
# baseline (speedup 1.0000x reference)
.LBB0_1223:
	s_and_saveexec_b64 s[6:7], s[4:5]
	s_cbranch_execz .LBB0_1227
	s_mov_b64 s[10:11], exec
	v_mbcnt_lo_u32_b32 v0, s10, 0
	v_mbcnt_hi_u32_b32 v0, s11, v0
	v_cmp_eq_u32_e32 vcc, 0, v0
	s_and_saveexec_b64 s[8:9], vcc
	s_cbranch_execz .LBB0_1226
	s_bcnt1_i32_b64 s10, s[10:11]
	v_mov_b32_e32 v1, s10
	v_mov_b32_e32 v2, 0x20004
	ds_read_b32 v2, v2
	v_readlane_b32 s100, v252, 0
	s_waitcnt lgkmcnt(0)
	v_readfirstlane_b32 s101, v2
	s_cmp_eq_u32 s101, 8
	s_cselect_b32 s101, 1, 0
	s_mul_i32 s100, s100, s101
	s_lshl_b32 s98, s100, 5
	v_mov_b32_e32 v2, s98
	global_atomic_add v1, v2, v1, s[42:43] sc0
.LBB0_1226:
	s_or_b64 exec, exec, s[8:9]
	s_waitcnt vmcnt(0)
	v_readfirstlane_b32 s8, v1
	s_cmp_eq_u32 s101, 0
	s_cbranch_scc1 .Lxq_done
	s_cmp_lt_u32 s8, 0x80
	s_cbranch_scc1 .Lxq_in
	s_movk_i32 s8, 0x400
	s_branch .Lxq_done
.Lxq_in:
	s_cmp_lt_u32 s8, 0x60
	s_cbranch_scc1 .Lxq_causal
	s_sub_u32 s8, s8, 0x60
	s_lshl_b32 s8, s8, 3
	s_add_u32 s8, s8, s100
	s_add_u32 s8, s8, 0x300
	s_branch .Lxq_done
.Lxq_causal:
	s_mul_i32 s10, s8, 43
	s_lshr_b32 s10, s10, 8
	s_mul_i32 s98, s10, 6
	s_sub_u32 s8, s8, s98
	s_lshl_b32 s8, s8, 3
	s_add_u32 s8, s8, s100
	s_mul_i32 s10, s10, 48
	s_add_u32 s8, s8, s10
.Lxq_done:
	v_mov_b32_e32 v1, s71
	s_nop 0
	v_add_u32_e32 v0, s8, v0
	ds_write_b32 v1, v0
